# v87 + nt on the bf16 weight stores of the conversion items (P0 and G1 slot)
# baseline (speedup 1.0000x reference)
; #define LAS __attribute__((address_space(3)))
; #define LDS_WAIT() asm volatile("s_waitcnt lgkmcnt(0)" ::: "memory")
; __device__ __forceinline__ unsigned pk2(float lo, float hi) { return pg8::cvt_pk_bf16(lo, hi); }
; __device__ __forceinline__ void item_store(const TItem& t, LAS float* scr, int lane) {
;     ...
;     for (int j = 0; j < 8; ++j) { const int n = nn + 8 * j; const LAS float* s = scr + (8 * c) * 65 + n;
;         v4u o; o.x = pk2(s[0 * 65], s[1 * 65]); o.y = pk2(s[2 * 65], s[3 * 65]); o.z = pk2(s[4 * 65], s[5 * 65]); o.w = pk2(s[6 * 65], s[7 * 65]);
;         *(v4u*)(t.WT + (size_t)rowmap(t.mode, n0 + n) * t.K + k0 + 8 * c) = o; }
;     ...
;             item_store(cur, scr, lane);
;             LDS_WAIT(); asm volatile("" ::: "memory");
;             if (!hn) break;
;             cur = nxt; kv = kvn; it = itn;
.LBB0_48:
	s_waitcnt lgkmcnt(3)
	v_cvt_pk_bf16_f32 v4, v4, v5
	s_waitcnt lgkmcnt(2)
	v_cvt_pk_bf16_f32 v5, v6, v7
	s_waitcnt lgkmcnt(1)
	v_cvt_pk_bf16_f32 v6, v8, v9
	v_mad_u64_u32 v[8:9], s[12:13], v94, s16, 0
	s_waitcnt lgkmcnt(0)
	v_cvt_pk_bf16_f32 v7, v10, v11
	v_ashrrev_i32_e32 v1, 31, v94
	v_mov_b32_e32 v10, v9
	v_mad_u64_u32 v[10:11], s[12:13], v1, s16, v[10:11]
	v_mov_b32_e32 v9, v10
	v_lshl_add_u64 v[8:9], v[8:9], 1, s[0:1]
	v_lshl_add_u64 v[8:9], s[8:9], 1, v[8:9]
	v_mov_b32_e32 v1, v3
	v_lshl_add_u64 v[8:9], v[8:9], 0, v[0:1]
	global_store_dwordx4 v[8:9], v[4:7], off nt
	s_waitcnt lgkmcnt(0)
	s_andn2_b64 vcc, exec, s[28:29]
	s_mov_b32 s24, s25
	s_mov_b32 s17, s27
	s_mov_b32 s8, s6
	s_mov_b32 s16, s26
	s_mov_b64 s[0:1], s[30:31]
	s_cbranch_vccz .LBB0_148

; #define LAS __attribute__((address_space(3)))
; __device__ __forceinline__ unsigned pk2(float lo, float hi) { return pg8::cvt_pk_bf16(lo, hi); }
; __device__ __forceinline__ void item_store(const TItem& t, LAS float* scr, int lane) {
;     ...
;     for (int j = 0; j < 8; ++j) { const int n = nn + 8 * j; const LAS float* s = scr + (8 * c) * 65 + n;
;         v4u o; o.x = pk2(s[0 * 65], s[1 * 65]); o.y = pk2(s[2 * 65], s[3 * 65]); o.z = pk2(s[4 * 65], s[5 * 65]); o.w = pk2(s[6 * 65], s[7 * 65]);
;         *(v4u*)(t.WT + (size_t)rowmap(t.mode, n0 + n) * t.K + k0 + 8 * c) = o; }
.LBB0_92:
	s_lshl_b32 s8, s12, 6
	s_waitcnt lgkmcnt(3)
	v_cvt_pk_bf16_f32 v4, v4, v5
	s_waitcnt lgkmcnt(2)
	v_cvt_pk_bf16_f32 v5, v6, v7
	s_waitcnt lgkmcnt(1)
	v_cvt_pk_bf16_f32 v6, v8, v9
	v_mad_u64_u32 v[8:9], s[12:13], v95, s16, 0
	s_waitcnt lgkmcnt(0)
	v_cvt_pk_bf16_f32 v7, v10, v11
	v_ashrrev_i32_e32 v1, 31, v95
	v_mov_b32_e32 v10, v9
	v_mad_u64_u32 v[10:11], s[12:13], v1, s16, v[10:11]
	v_mov_b32_e32 v9, v10
	s_ashr_i32 s9, s8, 31
	v_lshl_add_u64 v[8:9], v[8:9], 1, s[0:1]
	v_lshl_add_u64 v[8:9], s[8:9], 1, v[8:9]
	v_mov_b32_e32 v1, v3
	v_lshl_add_u64 v[8:9], v[8:9], 0, v[0:1]
	global_store_dwordx4 v[8:9], v[4:7], off nt
	ds_read2_b32 v[4:5], v16 offset0:8 offset1:73
	ds_read2_b32 v[6:7], v16 offset0:138 offset1:203
	ds_read2_b32 v[8:9], v94 offset0:12 offset1:77
	ds_read2_b32 v[10:11], v94 offset0:142 offset1:207
	v_or_b32_e32 v1, s24, v17
	s_cmp_lt_i32 s17, 2
	s_mov_b64 s[12:13], -1
	s_cbranch_scc1 .LBB0_96
	s_cmp_eq_u32 s17, 2
	v_mov_b32_e32 v95, v1
	s_cbranch_scc0 .LBB0_95
	v_cmp_lt_i32_e32 vcc, s18, v1
	s_nop 1
	v_cndmask_b32_e32 v95, 0, v28, vcc
	v_add_lshl_u32 v95, v95, v1, 1
	v_cndmask_b32_e64 v96, 0, 16, vcc
	v_and_b32_e32 v95, 0xffffff00, v95
	v_and_or_b32 v96, v1, s19, v96
	v_or3_b32 v95, v96, v95, v24

; #define LAS __attribute__((address_space(3)))
; __device__ __forceinline__ unsigned pk2(float lo, float hi) { return pg8::cvt_pk_bf16(lo, hi); }
; __device__ __forceinline__ void item_store(const TItem& t, LAS float* scr, int lane) {
;     ...
;     for (int j = 0; j < 8; ++j) { const int n = nn + 8 * j; const LAS float* s = scr + (8 * c) * 65 + n;
;         v4u o; o.x = pk2(s[0 * 65], s[1 * 65]); o.y = pk2(s[2 * 65], s[3 * 65]); o.z = pk2(s[4 * 65], s[5 * 65]); o.w = pk2(s[6 * 65], s[7 * 65]);
;         *(v4u*)(t.WT + (size_t)rowmap(t.mode, n0 + n) * t.K + k0 + 8 * c) = o; }
.LBB0_100:
	s_waitcnt lgkmcnt(3)
	v_cvt_pk_bf16_f32 v4, v4, v5
	s_waitcnt lgkmcnt(2)
	v_cvt_pk_bf16_f32 v5, v6, v7
	s_waitcnt lgkmcnt(1)
	v_cvt_pk_bf16_f32 v6, v8, v9
	v_mad_u64_u32 v[8:9], s[12:13], v95, s16, 0
	s_waitcnt lgkmcnt(0)
	v_cvt_pk_bf16_f32 v7, v10, v11
	v_ashrrev_i32_e32 v1, 31, v95
	v_mov_b32_e32 v10, v9
	v_mad_u64_u32 v[10:11], s[12:13], v1, s16, v[10:11]
	v_mov_b32_e32 v9, v10
	v_lshl_add_u64 v[8:9], v[8:9], 1, s[0:1]
	v_lshl_add_u64 v[8:9], s[8:9], 1, v[8:9]
	v_mov_b32_e32 v1, v3
	v_lshl_add_u64 v[8:9], v[8:9], 0, v[0:1]
	global_store_dwordx4 v[8:9], v[4:7], off nt
	ds_read2_b32 v[4:5], v16 offset0:16 offset1:81
	ds_read2_b32 v[6:7], v16 offset0:146 offset1:211
	ds_read2_b32 v[8:9], v94 offset0:20 offset1:85
	ds_read2_b32 v[10:11], v94 offset0:150 offset1:215
	v_or_b32_e32 v1, s24, v18
	s_cmp_lt_i32 s17, 2
	s_mov_b64 s[12:13], -1
	s_cbranch_scc1 .LBB0_104
	s_cmp_eq_u32 s17, 2
	v_mov_b32_e32 v95, v1
	s_cbranch_scc0 .LBB0_103
	v_cmp_lt_i32_e32 vcc, s18, v1
	s_nop 1
	v_cndmask_b32_e32 v95, 0, v28, vcc
	v_add_lshl_u32 v95, v95, v1, 1
	v_cndmask_b32_e64 v96, 0, 16, vcc
	v_and_b32_e32 v95, 0xffffff00, v95
	v_and_or_b32 v96, v1, s19, v96
	v_or3_b32 v95, v96, v95, v25

; #define LAS __attribute__((address_space(3)))
; __device__ __forceinline__ unsigned pk2(float lo, float hi) { return pg8::cvt_pk_bf16(lo, hi); }
; __device__ __forceinline__ void item_store(const TItem& t, LAS float* scr, int lane) {
;     ...
;     for (int j = 0; j < 8; ++j) { const int n = nn + 8 * j; const LAS float* s = scr + (8 * c) * 65 + n;
;         v4u o; o.x = pk2(s[0 * 65], s[1 * 65]); o.y = pk2(s[2 * 65], s[3 * 65]); o.z = pk2(s[4 * 65], s[5 * 65]); o.w = pk2(s[6 * 65], s[7 * 65]);
;         *(v4u*)(t.WT + (size_t)rowmap(t.mode, n0 + n) * t.K + k0 + 8 * c) = o; }
.LBB0_108:
	s_waitcnt lgkmcnt(3)
	v_cvt_pk_bf16_f32 v4, v4, v5
	s_waitcnt lgkmcnt(2)
	v_cvt_pk_bf16_f32 v5, v6, v7
	s_waitcnt lgkmcnt(1)
	v_cvt_pk_bf16_f32 v6, v8, v9
	v_mad_u64_u32 v[8:9], s[12:13], v95, s16, 0
	s_waitcnt lgkmcnt(0)
	v_cvt_pk_bf16_f32 v7, v10, v11
	v_ashrrev_i32_e32 v1, 31, v95
	v_mov_b32_e32 v10, v9
	v_mad_u64_u32 v[10:11], s[12:13], v1, s16, v[10:11]
	v_mov_b32_e32 v9, v10
	v_lshl_add_u64 v[8:9], v[8:9], 1, s[0:1]
	v_lshl_add_u64 v[8:9], s[8:9], 1, v[8:9]
	v_mov_b32_e32 v1, v3
	v_lshl_add_u64 v[8:9], v[8:9], 0, v[0:1]
	global_store_dwordx4 v[8:9], v[4:7], off nt
	ds_read2_b32 v[4:5], v16 offset0:24 offset1:89
	ds_read2_b32 v[6:7], v16 offset0:154 offset1:219
	ds_read2_b32 v[8:9], v94 offset0:28 offset1:93
	ds_read2_b32 v[10:11], v94 offset0:158 offset1:223
	v_or_b32_e32 v1, s24, v19
	s_cmp_lt_i32 s17, 2
	s_mov_b64 s[12:13], -1
	s_cbranch_scc1 .LBB0_112
	s_cmp_eq_u32 s17, 2
	v_mov_b32_e32 v95, v1
	s_cbranch_scc0 .LBB0_111
	v_cmp_lt_i32_e32 vcc, s18, v1
	s_nop 1
	v_cndmask_b32_e32 v95, 0, v28, vcc
	v_add_lshl_u32 v95, v95, v1, 1
	v_cndmask_b32_e64 v96, 0, 16, vcc
	v_and_b32_e32 v95, 0xffffff00, v95
	v_and_or_b32 v96, v1, s19, v96
	v_or3_b32 v95, v96, v95, v26

; #define LAS __attribute__((address_space(3)))
; __device__ __forceinline__ unsigned pk2(float lo, float hi) { return pg8::cvt_pk_bf16(lo, hi); }
; __device__ __forceinline__ void item_store(const TItem& t, LAS float* scr, int lane) {
;     ...
;     for (int j = 0; j < 8; ++j) { const int n = nn + 8 * j; const LAS float* s = scr + (8 * c) * 65 + n;
;         v4u o; o.x = pk2(s[0 * 65], s[1 * 65]); o.y = pk2(s[2 * 65], s[3 * 65]); o.z = pk2(s[4 * 65], s[5 * 65]); o.w = pk2(s[6 * 65], s[7 * 65]);
;         *(v4u*)(t.WT + (size_t)rowmap(t.mode, n0 + n) * t.K + k0 + 8 * c) = o; }
.LBB0_116:
	s_waitcnt lgkmcnt(3)
	v_cvt_pk_bf16_f32 v4, v4, v5
	s_waitcnt lgkmcnt(2)
	v_cvt_pk_bf16_f32 v5, v6, v7
	s_waitcnt lgkmcnt(1)
	v_cvt_pk_bf16_f32 v6, v8, v9
	v_mad_u64_u32 v[8:9], s[12:13], v95, s16, 0
	s_waitcnt lgkmcnt(0)
	v_cvt_pk_bf16_f32 v7, v10, v11
	v_ashrrev_i32_e32 v1, 31, v95
	v_mov_b32_e32 v10, v9
	v_mad_u64_u32 v[10:11], s[12:13], v1, s16, v[10:11]
	v_mov_b32_e32 v9, v10
	v_lshl_add_u64 v[8:9], v[8:9], 1, s[0:1]
	v_lshl_add_u64 v[8:9], s[8:9], 1, v[8:9]
	v_mov_b32_e32 v1, v3
	v_lshl_add_u64 v[8:9], v[8:9], 0, v[0:1]
	global_store_dwordx4 v[8:9], v[4:7], off nt
	ds_read2_b32 v[4:5], v16 offset0:32 offset1:97
	ds_read2_b32 v[6:7], v16 offset0:162 offset1:227
	ds_read2_b32 v[8:9], v94 offset0:36 offset1:101
	ds_read2_b32 v[10:11], v94 offset0:166 offset1:231
	v_or_b32_e32 v1, s24, v20
	s_cmp_lt_i32 s17, 2
	s_mov_b64 s[12:13], -1
	s_cbranch_scc1 .LBB0_120
	s_cmp_eq_u32 s17, 2
	v_mov_b32_e32 v95, v1
	s_cbranch_scc0 .LBB0_119
	v_cmp_lt_i32_e32 vcc, s18, v1
	s_nop 1
	v_cndmask_b32_e32 v95, 0, v28, vcc
	v_add_lshl_u32 v95, v95, v1, 1
	v_cndmask_b32_e64 v96, 0, 16, vcc
	v_and_b32_e32 v95, 0xffffff00, v95
	v_and_or_b32 v96, v1, s22, v96
	v_or3_b32 v95, v96, v95, v15

; #define LAS __attribute__((address_space(3)))
; __device__ __forceinline__ unsigned pk2(float lo, float hi) { return pg8::cvt_pk_bf16(lo, hi); }
; __device__ __forceinline__ void item_store(const TItem& t, LAS float* scr, int lane) {
;     ...
;     for (int j = 0; j < 8; ++j) { const int n = nn + 8 * j; const LAS float* s = scr + (8 * c) * 65 + n;
;         v4u o; o.x = pk2(s[0 * 65], s[1 * 65]); o.y = pk2(s[2 * 65], s[3 * 65]); o.z = pk2(s[4 * 65], s[5 * 65]); o.w = pk2(s[6 * 65], s[7 * 65]);
;         *(v4u*)(t.WT + (size_t)rowmap(t.mode, n0 + n) * t.K + k0 + 8 * c) = o; }
.LBB0_124:
	s_waitcnt lgkmcnt(3)
	v_cvt_pk_bf16_f32 v4, v4, v5
	s_waitcnt lgkmcnt(2)
	v_cvt_pk_bf16_f32 v5, v6, v7
	s_waitcnt lgkmcnt(1)
	v_cvt_pk_bf16_f32 v6, v8, v9
	v_mad_u64_u32 v[8:9], s[12:13], v95, s16, 0
	s_waitcnt lgkmcnt(0)
	v_cvt_pk_bf16_f32 v7, v10, v11
	v_ashrrev_i32_e32 v1, 31, v95
	v_mov_b32_e32 v10, v9
	v_mad_u64_u32 v[10:11], s[12:13], v1, s16, v[10:11]
	v_mov_b32_e32 v9, v10
	v_lshl_add_u64 v[8:9], v[8:9], 1, s[0:1]
	v_lshl_add_u64 v[8:9], s[8:9], 1, v[8:9]
	v_mov_b32_e32 v1, v3
	v_lshl_add_u64 v[8:9], v[8:9], 0, v[0:1]
	global_store_dwordx4 v[8:9], v[4:7], off nt
	ds_read2_b32 v[4:5], v16 offset0:40 offset1:105
	ds_read2_b32 v[6:7], v16 offset0:170 offset1:235
	ds_read2_b32 v[8:9], v94 offset0:44 offset1:109
	ds_read2_b32 v[10:11], v94 offset0:174 offset1:239
	v_or_b32_e32 v1, s24, v21
	s_cmp_lt_i32 s17, 2
	s_mov_b64 s[12:13], -1
	s_cbranch_scc1 .LBB0_128
	s_cmp_eq_u32 s17, 2
	v_mov_b32_e32 v95, v1
	s_cbranch_scc0 .LBB0_127
	v_cmp_lt_i32_e32 vcc, s18, v1
	s_nop 1
	v_cndmask_b32_e32 v95, 0, v28, vcc
	v_add_lshl_u32 v95, v95, v1, 1
	v_cndmask_b32_e64 v96, 0, 16, vcc
	v_and_b32_e32 v95, 0xffffff00, v95
	v_and_or_b32 v96, v1, s22, v96
	v_or3_b32 v95, v96, v95, v24

; #define LAS __attribute__((address_space(3)))
; __device__ __forceinline__ unsigned pk2(float lo, float hi) { return pg8::cvt_pk_bf16(lo, hi); }
; __device__ __forceinline__ void item_store(const TItem& t, LAS float* scr, int lane) {
;     ...
;     for (int j = 0; j < 8; ++j) { const int n = nn + 8 * j; const LAS float* s = scr + (8 * c) * 65 + n;
;         v4u o; o.x = pk2(s[0 * 65], s[1 * 65]); o.y = pk2(s[2 * 65], s[3 * 65]); o.z = pk2(s[4 * 65], s[5 * 65]); o.w = pk2(s[6 * 65], s[7 * 65]);
;         *(v4u*)(t.WT + (size_t)rowmap(t.mode, n0 + n) * t.K + k0 + 8 * c) = o; }
.LBB0_132:
	s_waitcnt lgkmcnt(3)
	v_cvt_pk_bf16_f32 v4, v4, v5
	s_waitcnt lgkmcnt(2)
	v_cvt_pk_bf16_f32 v5, v6, v7
	s_waitcnt lgkmcnt(1)
	v_cvt_pk_bf16_f32 v6, v8, v9
	v_mad_u64_u32 v[8:9], s[12:13], v95, s16, 0
	s_waitcnt lgkmcnt(0)
	v_cvt_pk_bf16_f32 v7, v10, v11
	v_ashrrev_i32_e32 v1, 31, v95
	v_mov_b32_e32 v10, v9
	v_mad_u64_u32 v[10:11], s[12:13], v1, s16, v[10:11]
	v_mov_b32_e32 v9, v10
	v_lshl_add_u64 v[8:9], v[8:9], 1, s[0:1]
	v_lshl_add_u64 v[8:9], s[8:9], 1, v[8:9]
	v_mov_b32_e32 v1, v3
	v_lshl_add_u64 v[8:9], v[8:9], 0, v[0:1]
	global_store_dwordx4 v[8:9], v[4:7], off nt
	ds_read2_b32 v[4:5], v16 offset0:48 offset1:113
	ds_read2_b32 v[6:7], v16 offset0:178 offset1:243
	ds_read2_b32 v[8:9], v94 offset0:52 offset1:117
	ds_read2_b32 v[10:11], v94 offset0:182 offset1:247
	v_or_b32_e32 v1, s24, v22
	s_cmp_lt_i32 s17, 2
	s_mov_b64 s[12:13], -1
	s_cbranch_scc1 .LBB0_136
	s_cmp_eq_u32 s17, 2
	v_mov_b32_e32 v95, v1
	s_cbranch_scc0 .LBB0_135
	v_cmp_lt_i32_e32 vcc, s18, v1
	s_nop 1
	v_cndmask_b32_e32 v95, 0, v28, vcc
	v_add_lshl_u32 v95, v95, v1, 1
	v_cndmask_b32_e64 v96, 0, 16, vcc
	v_and_b32_e32 v95, 0xffffff00, v95
	v_and_or_b32 v96, v1, s22, v96
	v_or3_b32 v95, v96, v95, v25

; #define LAS __attribute__((address_space(3)))
; __device__ __forceinline__ unsigned pk2(float lo, float hi) { return pg8::cvt_pk_bf16(lo, hi); }
; __device__ __forceinline__ void item_store(const TItem& t, LAS float* scr, int lane) {
;     ...
;     for (int j = 0; j < 8; ++j) { const int n = nn + 8 * j; const LAS float* s = scr + (8 * c) * 65 + n;
;         v4u o; o.x = pk2(s[0 * 65], s[1 * 65]); o.y = pk2(s[2 * 65], s[3 * 65]); o.z = pk2(s[4 * 65], s[5 * 65]); o.w = pk2(s[6 * 65], s[7 * 65]);
;         *(v4u*)(t.WT + (size_t)rowmap(t.mode, n0 + n) * t.K + k0 + 8 * c) = o; }
.LBB0_140:
	s_waitcnt lgkmcnt(3)
	v_cvt_pk_bf16_f32 v4, v4, v5
	s_waitcnt lgkmcnt(2)
	v_cvt_pk_bf16_f32 v5, v6, v7
	s_waitcnt lgkmcnt(1)
	v_cvt_pk_bf16_f32 v6, v8, v9
	v_mad_u64_u32 v[8:9], s[12:13], v95, s16, 0
	s_waitcnt lgkmcnt(0)
	v_cvt_pk_bf16_f32 v7, v10, v11
	v_ashrrev_i32_e32 v1, 31, v95
	v_mov_b32_e32 v10, v9
	v_mad_u64_u32 v[10:11], s[12:13], v1, s16, v[10:11]
	v_mov_b32_e32 v9, v10
	v_lshl_add_u64 v[8:9], v[8:9], 1, s[0:1]
	v_lshl_add_u64 v[8:9], s[8:9], 1, v[8:9]
	v_mov_b32_e32 v1, v3
	v_lshl_add_u64 v[8:9], v[8:9], 0, v[0:1]
	global_store_dwordx4 v[8:9], v[4:7], off nt
	ds_read2_b32 v[4:5], v16 offset0:56 offset1:121
	ds_read2_b32 v[6:7], v16 offset0:186 offset1:251
	ds_read2_b32 v[8:9], v94 offset0:60 offset1:125
	ds_read2_b32 v[10:11], v94 offset0:190 offset1:255
	v_or_b32_e32 v1, s24, v23
	s_cmp_lt_i32 s17, 2
	s_mov_b64 s[12:13], -1
	s_cbranch_scc1 .LBB0_144
	s_cmp_eq_u32 s17, 2
	v_mov_b32_e32 v94, v1
	s_cbranch_scc0 .LBB0_143
	v_cmp_lt_i32_e32 vcc, s18, v1
	s_nop 1
	v_cndmask_b32_e32 v94, 0, v28, vcc
	v_add_lshl_u32 v94, v94, v1, 1
	v_cndmask_b32_e64 v95, 0, 16, vcc
	v_and_b32_e32 v94, 0xffffff00, v94
	v_and_or_b32 v95, v1, s22, v95
	v_or3_b32 v94, v95, v94, v26

; __device__ __forceinline__ void prologue(const Params& P, LAS unsigned char* L, int gw, int NGW, int wave, int lane, int nitems) {
;     ...
;     { constexpr int PADV = (NP - DIN) * D * 2 / 16;
;       const int gt = gw * 64 + lane, NT = NGW * 64;
;       for (int i = gt; i < DEPTH * PADV; i += NT) { const int layer = i / PADV, j = i - layer * PADV;
;           *((v4u*)(ws + WS_W + (size_t)layer * WL_STRIDE + WL_WIN + (size_t)DIN * D * 2) + j) = (v4u){0u, 0u, 0u, 0u}; }
.LBB0_150:
	v_mul_hi_i32 v7, v6, s5
	v_lshrrev_b32_e32 v8, 31, v7
	v_ashrrev_i32_e32 v7, 13, v7
	v_add_u32_e32 v7, v7, v8
	v_mad_i32_i24 v8, v7, s8, v6
	v_mad_i64_i32 v[10:11], s[12:13], v7, s9, v[4:5]
	v_add_u32_e32 v6, s36, v6
	v_ashrrev_i32_e32 v9, 31, v8
	v_cmp_lt_i32_e32 vcc, s10, v6
	v_lshl_add_u64 v[8:9], v[8:9], 4, v[10:11]
	s_or_b64 s[6:7], vcc, s[6:7]
	v_add_co_u32_e32 v8, vcc, 0x5140000, v8
	s_nop 1
	v_addc_co_u32_e32 v9, vcc, 0, v9, vcc
	global_store_dwordx4 v[8:9], v[0:3], off nt
	s_andn2_b64 exec, exec, s[6:7]
	s_cbranch_execnz .LBB0_150

; __device__ __forceinline__ unsigned pk2(float lo, float hi) { return pg8::cvt_pk_bf16(lo, hi); }
; __device__ __forceinline__ void prologue(const Params& P, LAS unsigned char* L, int gw, int NGW, int wave, int lane, int nitems) {
;     ...
;       const f32x4* ps = (const f32x4*)P.p; v2u* pd = (v2u*)(ws + WS_PBF);
;       for (int i = gt; i < DEPTH * M * PLE / 4; i += NT) { const f32x4 v = ps[i]; v2u o; o.x = pk2(v[0], v[1]); o.y = pk2(v[2], v[3]); pd[i] = o; }
.Lp8_check:
	v_add_u32_e32 v5, s36, v4
	v_add_u32_e32 v5, s36, v5
	v_add_u32_e32 v5, s36, v5
	v_add_u32_e32 v5, s36, v5
	v_add_u32_e32 v5, s36, v5
	v_add_u32_e32 v5, s36, v5
	v_add_u32_e32 v5, s36, v5
	v_cmp_ge_i32_e32 vcc, s5, v5
	s_and_b64 vcc, vcc, exec
	s_cmp_eq_u64 vcc, exec
	s_cbranch_scc0 .Lp8_rem
	global_load_dwordx4 v[6:9], v[0:1], off
	v_lshl_add_u64 v[0:1], v[0:1], 0, s[6:7]
	global_load_dwordx4 v[14:17], v[0:1], off
	v_lshl_add_u64 v[0:1], v[0:1], 0, s[6:7]
	global_load_dwordx4 v[18:21], v[0:1], off
	v_lshl_add_u64 v[0:1], v[0:1], 0, s[6:7]
	global_load_dwordx4 v[22:25], v[0:1], off
	v_lshl_add_u64 v[0:1], v[0:1], 0, s[6:7]
	global_load_dwordx4 v[26:29], v[0:1], off
	v_lshl_add_u64 v[0:1], v[0:1], 0, s[6:7]
	global_load_dwordx4 v[52:55], v[0:1], off
	v_lshl_add_u64 v[0:1], v[0:1], 0, s[6:7]
	global_load_dwordx4 v[56:59], v[0:1], off
	v_lshl_add_u64 v[0:1], v[0:1], 0, s[6:7]
	global_load_dwordx4 v[60:63], v[0:1], off
	v_lshl_add_u64 v[0:1], v[0:1], 0, s[6:7]
	v_add_u32_e32 v4, s36, v5
	s_waitcnt vmcnt(7)
	v_cvt_pk_bf16_f32 v6, v6, v7
	v_cvt_pk_bf16_f32 v7, v8, v9
	global_store_dwordx2 v[2:3], v[6:7], off nt
	v_lshl_add_u64 v[2:3], v[2:3], 0, s[8:9]
	s_waitcnt vmcnt(7)
	v_cvt_pk_bf16_f32 v14, v14, v15
	v_cvt_pk_bf16_f32 v15, v16, v17
	global_store_dwordx2 v[2:3], v[14:15], off nt
	v_lshl_add_u64 v[2:3], v[2:3], 0, s[8:9]
	s_waitcnt vmcnt(7)
	v_cvt_pk_bf16_f32 v18, v18, v19
	v_cvt_pk_bf16_f32 v19, v20, v21
	global_store_dwordx2 v[2:3], v[18:19], off nt
	v_lshl_add_u64 v[2:3], v[2:3], 0, s[8:9]
	s_waitcnt vmcnt(7)
	v_cvt_pk_bf16_f32 v22, v22, v23
	v_cvt_pk_bf16_f32 v23, v24, v25
	global_store_dwordx2 v[2:3], v[22:23], off nt
	v_lshl_add_u64 v[2:3], v[2:3], 0, s[8:9]
	s_waitcnt vmcnt(7)
	v_cvt_pk_bf16_f32 v26, v26, v27
	v_cvt_pk_bf16_f32 v27, v28, v29
	global_store_dwordx2 v[2:3], v[26:27], off nt
	v_lshl_add_u64 v[2:3], v[2:3], 0, s[8:9]
	s_waitcnt vmcnt(7)
	v_cvt_pk_bf16_f32 v52, v52, v53
	v_cvt_pk_bf16_f32 v53, v54, v55
	global_store_dwordx2 v[2:3], v[52:53], off nt
	v_lshl_add_u64 v[2:3], v[2:3], 0, s[8:9]
	s_waitcnt vmcnt(7)
	v_cvt_pk_bf16_f32 v56, v56, v57
	v_cvt_pk_bf16_f32 v57, v58, v59
	global_store_dwordx2 v[2:3], v[56:57], off nt
	v_lshl_add_u64 v[2:3], v[2:3], 0, s[8:9]
	s_waitcnt vmcnt(7)
	v_cvt_pk_bf16_f32 v60, v60, v61
	v_cvt_pk_bf16_f32 v61, v62, v63
	global_store_dwordx2 v[2:3], v[60:61], off nt
	v_lshl_add_u64 v[2:3], v[2:3], 0, s[8:9]
	s_branch .Lp8_check

; __device__ __forceinline__ unsigned pk2(float lo, float hi) { return pg8::cvt_pk_bf16(lo, hi); }
; __device__ __forceinline__ void prologue(const Params& P, LAS unsigned char* L, int gw, int NGW, int wave, int lane, int nitems) {
;     ...
;       for (int i = gt; i < DEPTH * M * PLE / 4; i += NT) { const f32x4 v = ps[i]; v2u o; o.x = pk2(v[0], v[1]); o.y = pk2(v[2], v[3]); pd[i] = o; }
.LBB0_153:
	global_load_dwordx4 v[6:9], v[0:1], off
	v_add_u32_e32 v4, s36, v4
	v_cmp_lt_i32_e32 vcc, s5, v4
	v_lshl_add_u64 v[0:1], v[0:1], 0, s[6:7]
	s_or_b64 s[10:11], vcc, s[10:11]
	s_waitcnt vmcnt(0)
	v_cvt_pk_bf16_f32 v6, v6, v7
	v_cvt_pk_bf16_f32 v7, v8, v9
	global_store_dwordx2 v[2:3], v[6:7], off nt
	v_lshl_add_u64 v[2:3], v[2:3], 0, s[8:9]
	s_andn2_b64 exec, exec, s[10:11]
	s_cbranch_execnz .LBB0_153

; __device__ __forceinline__ void rmsnorm_row_copy_bf16(const float* xrow, const float* g, pg8::h16_t* hrow, bf16* orow, int lane) {
;     const f32x4* xr = (const f32x4*)xrow + lane; pg8::h16x4* hr = (pg8::h16x4*)hrow + lane; f32x4 v[8]; float s = 0.f;
; #pragma unroll
;     for (int j = 0; j < 8; ++j) { v[j] = xr[64 * j]; hr[64 * j] = __builtin_convertvector(v[j], pg8::h16x4); s += (v[j][0] * v[j][0] + v[j][1] * v[j][1]) + (v[j][2] * v[j][2] + v[j][3] * v[j][3]); }
.LBB0_156:
	global_load_dwordx4 v[8:11], v[44:45], off offset:-4096
	global_load_dwordx4 v[0:3], v[44:45], off offset:-3072
	global_load_dwordx4 v[16:19], v[44:45], off offset:-2048
	global_load_dwordx4 v[20:23], v[44:45], off offset:-1024
	global_load_dwordx4 v[12:15], v[44:45], off
	global_load_dwordx4 v[24:27], v[44:45], off offset:1024
	global_load_dwordx4 v[28:31], v[44:45], off offset:2048
	global_load_dwordx4 v[4:7], v[44:45], off offset:3072
	s_nop 0
	v_add_co_u32_e32 v62, vcc, s10, v46
	s_add_i32 s4, s4, s60
	s_nop 0
	v_addc_co_u32_e32 v63, vcc, 0, v47, vcc
	s_cmpk_gt_i32 s4, 0x1fff
	s_waitcnt vmcnt(7)
	v_cvt_pk_f16_f32 v117, v10, v11
	v_cvt_pk_f16_f32 v116, v8, v9
	global_store_dwordx2 v[46:47], v[116:117], off nt
	v_mov_b32_e32 v60, v9
	v_mov_b32_e32 v66, v11
	v_mov_b32_e32 v58, v8
	v_mov_b32_e32 v64, v10
	s_waitcnt vmcnt(7)
	v_cvt_pk_f16_f32 v117, v2, v3
	v_cvt_pk_f16_f32 v116, v0, v1
	global_store_dwordx2 v[46:47], v[116:117], off offset:512 nt
	v_mov_b32_e32 v61, v1
	v_mov_b32_e32 v67, v3
	v_mov_b32_e32 v59, v0
	v_mov_b32_e32 v65, v2
	v_pk_mul_f32 v[60:61], v[60:61], v[60:61]
	v_pk_mul_f32 v[66:67], v[66:67], v[66:67]
	v_pk_fma_f32 v[58:59], v[58:59], v[58:59], v[60:61]
	v_pk_fma_f32 v[60:61], v[64:65], v[64:65], v[66:67]
	s_waitcnt vmcnt(7)
	v_cvt_pk_f16_f32 v117, v18, v19
	v_cvt_pk_f16_f32 v116, v16, v17
	global_store_dwordx2 v[46:47], v[116:117], off offset:1024 nt
	v_pk_add_f32 v[58:59], v[58:59], v[60:61]
	v_pk_mul_f32 v[60:61], v[18:19], v[18:19]
	v_pk_mul_f32 v[64:65], v[16:17], v[16:17]
	v_pk_add_f32 v[58:59], v[58:59], v[58:59] op_sel:[0,1] op_sel_hi:[1,0]
	v_pk_mov_b32 v[66:67], v[64:65], v[60:61] op_sel:[1,0]
	v_mov_b32_e32 v65, v61
	v_pk_add_f32 v[60:61], v[66:67], v[64:65]
	s_waitcnt vmcnt(7)
	v_cvt_pk_f16_f32 v117, v22, v23
	v_cvt_pk_f16_f32 v116, v20, v21
	global_store_dwordx2 v[46:47], v[116:117], off offset:1536 nt
	v_mul_f32_e32 v64, v21, v21
	v_mul_f32_e32 v66, v23, v23
	v_pk_add_f32 v[60:61], v[60:61], v[60:61] op_sel:[0,1] op_sel_hi:[1,0]
	v_pk_fma_f32 v[64:65], v[20:21], v[20:21], v[64:65] op_sel_hi:[1,1,0]
	v_pk_fma_f32 v[66:67], v[22:23], v[22:23], v[66:67] op_sel_hi:[1,1,0]
	s_waitcnt vmcnt(7)
	v_cvt_pk_f16_f32 v117, v14, v15
	v_cvt_pk_f16_f32 v116, v12, v13
	global_store_dwordx2 v[46:47], v[116:117], off offset:2048 nt
	v_mul_f32_e32 v59, v12, v12
	v_mul_f32_e32 v61, v13, v13
	v_mul_f32_e32 v65, v14, v14
	v_mul_f32_e32 v67, v15, v15
	v_pk_add_f32 v[58:59], v[58:59], v[60:61]
	v_pk_add_f32 v[60:61], v[64:65], v[66:67]
	s_waitcnt vmcnt(7)
	v_cvt_pk_f16_f32 v117, v26, v27
	v_cvt_pk_f16_f32 v116, v24, v25
	global_store_dwordx2 v[46:47], v[116:117], off offset:2560 nt
	v_pk_add_f32 v[58:59], v[58:59], v[60:61]
	v_pk_mul_f32 v[60:61], v[24:25], v[24:25]
	v_pk_add_f32 v[64:65], v[58:59], v[58:59] op_sel:[0,1] op_sel_hi:[1,0]
	v_pk_mul_f32 v[58:59], v[26:27], v[26:27]
	s_waitcnt vmcnt(7)
	v_cvt_pk_f16_f32 v117, v30, v31
	v_cvt_pk_f16_f32 v116, v28, v29
	global_store_dwordx2 v[46:47], v[116:117], off offset:3072 nt
	v_pk_mov_b32 v[66:67], v[60:61], v[58:59] op_sel:[1,0]
	v_mov_b32_e32 v61, v59
	v_pk_add_f32 v[58:59], v[66:67], v[60:61]
	v_mul_f32_e32 v60, v31, v31
	v_pk_add_f32 v[66:67], v[58:59], v[58:59] op_sel:[0,1] op_sel_hi:[1,0]
	v_mul_f32_e32 v58, v29, v29
	v_pk_fma_f32 v[68:69], v[28:29], v[28:29], v[58:59] op_sel_hi:[1,1,0]
	v_pk_fma_f32 v[70:71], v[30:31], v[30:31], v[60:61] op_sel_hi:[1,1,0]
	v_lshl_add_u64 v[44:45], v[44:45], 0, s[6:7]
	s_waitcnt vmcnt(7)
	v_cvt_pk_f16_f32 v117, v6, v7
	v_cvt_pk_f16_f32 v116, v4, v5
	global_store_dwordx2 v[46:47], v[116:117], off offset:3584 nt
	v_mul_f32_e32 v65, v4, v4
	v_mul_f32_e32 v67, v5, v5
	v_mul_f32_e32 v69, v6, v6
	v_mul_f32_e32 v71, v7, v7
	v_pk_add_f32 v[64:65], v[64:65], v[66:67]
	v_pk_add_f32 v[66:67], v[68:69], v[70:71]
	v_lshl_add_u64 v[46:47], v[46:47], 0, s[8:9]
	v_pk_add_f32 v[64:65], v[64:65], v[66:67]
	s_nop 0
	v_add_f32_e32 v57, v64, v65
	ds_bpermute_b32 v64, v49, v57
	s_waitcnt lgkmcnt(0)
; __device__ __forceinline__ unsigned pk2(float lo, float hi) { return pg8::cvt_pk_bf16(lo, hi); }
; __device__ __forceinline__ void rmsnorm_row_copy_bf16(const float* xrow, const float* g, pg8::h16_t* hrow, bf16* orow, int lane) {
;     ...
;     const float rs = 1.0f / sqrtf(wave_sum(s) * (1.0f / D) + EPS);
;     const f32x4* gr = (const f32x4*)g + lane; v2u* o8 = (v2u*)orow + lane;
; #pragma unroll
;     for (int j = 0; j < 8; ++j) { const f32x4 gv = gr[64 * j]; v2u o; o.x = pk2(v[j][0] * rs * gv[0], v[j][1] * rs * gv[1]); o.y = pk2(v[j][2] * rs * gv[2], v[j][3] * rs * gv[3]); o8[64 * j] = o; }
	v_add_f32_e32 v57, v57, v64
	ds_bpermute_b32 v64, v50, v57
	s_waitcnt lgkmcnt(0)
	v_add_f32_e32 v57, v57, v64
	ds_bpermute_b32 v64, v51, v57
	s_waitcnt lgkmcnt(0)
	v_add_f32_e32 v57, v57, v64
	ds_bpermute_b32 v64, v52, v57
	s_waitcnt lgkmcnt(0)
	v_add_f32_e32 v57, v57, v64
	ds_bpermute_b32 v64, v53, v57
	s_waitcnt lgkmcnt(0)
	v_add_f32_e32 v57, v57, v64
	ds_bpermute_b32 v64, v54, v57
	s_waitcnt lgkmcnt(0)
	v_add_f32_e32 v57, v57, v64
	v_fmamk_f32 v57, v57, 0x3a000000, v55
	v_mul_f32_e32 v64, 0x4f800000, v57
	v_cmp_gt_f32_e32 vcc, s5, v57
	s_nop 1
	v_cndmask_b32_e32 v57, v57, v64, vcc
	v_sqrt_f32_e32 v64, v57
	s_nop 0
	v_add_u32_e32 v65, -1, v64
	v_add_u32_e32 v66, 1, v64
	v_fma_f32 v67, -v65, v64, v57
	v_fma_f32 v68, -v66, v64, v57
	v_cmp_ge_f32_e64 s[0:1], 0, v67
	s_nop 1
	v_cndmask_b32_e64 v64, v64, v65, s[0:1]
	v_cmp_lt_f32_e64 s[0:1], 0, v68
	s_nop 1
	v_cndmask_b32_e64 v64, v64, v66, s[0:1]
	v_mul_f32_e32 v65, 0x37800000, v64
	v_cndmask_b32_e32 v64, v64, v65, vcc
	v_cmp_class_f32_e32 vcc, v57, v56
	s_nop 1
	v_cndmask_b32_e32 v57, v64, v57, vcc
	v_div_scale_f32 v64, s[0:1], v57, v57, 1.0
	v_rcp_f32_e32 v66, v64
	v_div_scale_f32 v65, vcc, 1.0, v57, 1.0
	v_fma_f32 v67, -v64, v66, 1.0
	v_fmac_f32_e32 v66, v67, v66
	v_mul_f32_e32 v67, v65, v66
	v_fma_f32 v68, -v64, v67, v65
	v_fmac_f32_e32 v67, v68, v66
	v_fma_f32 v64, -v64, v67, v65
	v_div_fmas_f32 v64, v64, v66, v67
	v_div_fixup_f32 v64, v64, v57, 1.0
	v_pk_mul_f32 v[8:9], v[8:9], v[64:65] op_sel_hi:[1,0]
	v_pk_mul_f32 v[10:11], v[10:11], v[64:65] op_sel_hi:[1,0]
	v_pk_mul_f32 v[8:9], v[84:85], v[8:9]
	v_pk_mul_f32 v[10:11], v[86:87], v[10:11]
	v_cvt_pk_bf16_f32 v8, v8, v9
	v_cvt_pk_bf16_f32 v9, v10, v11
	global_store_dwordx2 v[62:63], v[8:9], off nt
	v_pk_mul_f32 v[0:1], v[0:1], v[64:65] op_sel_hi:[1,0]
	v_pk_mul_f32 v[2:3], v[2:3], v[64:65] op_sel_hi:[1,0]
	v_pk_mul_f32 v[4:5], v[4:5], v[64:65] op_sel_hi:[1,0]
	v_pk_mul_f32 v[6:7], v[6:7], v[64:65] op_sel_hi:[1,0]
	v_pk_mul_f32 v[0:1], v[88:89], v[0:1]
	v_pk_mul_f32 v[2:3], v[90:91], v[2:3]
	v_cvt_pk_bf16_f32 v0, v0, v1
	v_cvt_pk_bf16_f32 v1, v2, v3
	global_store_dwordx2 v[62:63], v[0:1], off offset:512 nt
	v_pk_mul_f32 v[8:9], v[16:17], v[64:65] op_sel_hi:[1,0]
	v_pk_mul_f32 v[10:11], v[18:19], v[64:65] op_sel_hi:[1,0]
	v_pk_mul_f32 v[0:1], v[92:93], v[8:9]
	v_pk_mul_f32 v[2:3], v[94:95], v[10:11]
	v_cvt_pk_bf16_f32 v0, v0, v1
	v_cvt_pk_bf16_f32 v1, v2, v3
	global_store_dwordx2 v[62:63], v[0:1], off offset:1024 nt
	v_pk_mul_f32 v[8:9], v[20:21], v[64:65] op_sel_hi:[1,0]
	v_pk_mul_f32 v[10:11], v[22:23], v[64:65] op_sel_hi:[1,0]
	v_pk_mul_f32 v[0:1], v[96:97], v[8:9]
	v_pk_mul_f32 v[2:3], v[98:99], v[10:11]
	v_cvt_pk_bf16_f32 v0, v0, v1
	v_cvt_pk_bf16_f32 v1, v2, v3
	global_store_dwordx2 v[62:63], v[0:1], off offset:1536 nt
	v_pk_mul_f32 v[8:9], v[12:13], v[64:65] op_sel_hi:[1,0]
	v_pk_mul_f32 v[10:11], v[14:15], v[64:65] op_sel_hi:[1,0]
	v_pk_mul_f32 v[0:1], v[8:9], v[100:101]
	v_pk_mul_f32 v[2:3], v[10:11], v[102:103]
	v_cvt_pk_bf16_f32 v0, v0, v1
	v_cvt_pk_bf16_f32 v1, v2, v3
	global_store_dwordx2 v[62:63], v[0:1], off offset:2048 nt
	v_pk_mul_f32 v[8:9], v[24:25], v[64:65] op_sel_hi:[1,0]
	v_pk_mul_f32 v[10:11], v[26:27], v[64:65] op_sel_hi:[1,0]
	v_pk_mul_f32 v[0:1], v[8:9], v[104:105]
	v_pk_mul_f32 v[2:3], v[10:11], v[106:107]
	v_cvt_pk_bf16_f32 v0, v0, v1
	v_cvt_pk_bf16_f32 v1, v2, v3
	global_store_dwordx2 v[62:63], v[0:1], off offset:2560 nt
	v_pk_mul_f32 v[8:9], v[28:29], v[64:65] op_sel_hi:[1,0]
	v_pk_mul_f32 v[10:11], v[30:31], v[64:65] op_sel_hi:[1,0]
	v_pk_mul_f32 v[0:1], v[8:9], v[108:109]
	v_pk_mul_f32 v[2:3], v[10:11], v[110:111]
	v_cvt_pk_bf16_f32 v0, v0, v1
	v_cvt_pk_bf16_f32 v1, v2, v3
	global_store_dwordx2 v[62:63], v[0:1], off offset:3072 nt
	v_pk_mul_f32 v[0:1], v[4:5], v[112:113]
	v_pk_mul_f32 v[2:3], v[6:7], v[114:115]
	v_cvt_pk_bf16_f32 v0, v0, v1
	v_cvt_pk_bf16_f32 v1, v2, v3
	global_store_dwordx2 v[62:63], v[0:1], off offset:3584 nt
	s_cbranch_scc0 .LBB0_156

; __device__ __forceinline__ unsigned cvt_pk_bf16(float lo, float hi) { const f32x2_t v = {lo, hi}; const bf16x2_t c = __builtin_convertvector(v, bf16x2_t); return __builtin_bit_cast(unsigned, c); }
;     __device__ __forceinline__ void operator()(const f32x4 (&acc)[2][2][4][2], const Unit& u, int wr, int wc, int fr, int fq) const {
;         const int row0 = u.pm * BM + wr * 64 + fr, col0 = u.pn * BM + wc * 32 + 8 * fq;
; #pragma unroll
;         for (int ai = 0; ai < 2; ++ai)
; #pragma unroll
;             for (int m = 0; m < 4; ++m) { bf16_t* rowp = O + (size_t)(row0 + ai * HALF + m * 16) * ldc + col0;
; #pragma unroll
;                 for (int bj = 0; bj < 2; ++bj) { const f32x4 v0 = acc[ai][bj][m][0], v1 = acc[ai][bj][m][1];
;                     u32x4 w; w.x = cvt_pk_bf16(v0[0], v0[1]); w.y = cvt_pk_bf16(v0[2], v0[3]); w.z = cvt_pk_bf16(v1[0], v1[1]); w.w = cvt_pk_bf16(v1[2], v1[3]);
;                     *(u32x4*)(rowp + bj * HALF) = w; } }
.LBB0_266:
	v_lshl_add_u32 v150, s12, 8, v140
	v_lshl_or_b32 v144, s10, 8, v142
	v_ashrrev_i32_e32 v145, 31, v144
	v_mov_b64_e32 v[146:147], s[76:77]
	v_cvt_pk_bf16_f32 v70, v70, v71
	v_cvt_pk_bf16_f32 v71, v72, v73
	v_cvt_pk_bf16_f32 v72, v66, v67
	v_add_u32_e32 v66, 0x80, v150
	v_mad_i64_i32 v[148:149], s[10:11], v150, s67, v[146:147]
	v_lshlrev_b64 v[144:145], 1, v[144:145]
	v_cvt_pk_bf16_f32 v110, v110, v111
	v_cvt_pk_bf16_f32 v111, v112, v113
	v_cvt_pk_bf16_f32 v112, v106, v107
	v_or_b32_e32 v106, 16, v150
	v_mad_i64_i32 v[66:67], s[10:11], v66, s67, v[146:147]
	v_cvt_pk_bf16_f32 v46, v46, v47
	v_cvt_pk_bf16_f32 v47, v48, v49
	v_cvt_pk_bf16_f32 v48, v42, v43
	v_add_u32_e32 v42, 0x90, v150
	v_lshl_add_u64 v[148:149], v[148:149], 0, v[144:145]
	v_cvt_pk_bf16_f32 v113, v108, v109
	v_mad_i64_i32 v[106:107], s[10:11], v106, s67, v[146:147]
	v_cvt_pk_bf16_f32 v94, v94, v95
	v_cvt_pk_bf16_f32 v95, v96, v97
	v_cvt_pk_bf16_f32 v96, v90, v91
	v_or_b32_e32 v90, 32, v150
	v_lshl_add_u64 v[66:67], v[66:67], 0, v[144:145]
	v_cvt_pk_bf16_f32 v49, v44, v45
	v_mad_i64_i32 v[42:43], s[10:11], v42, s67, v[146:147]
	v_cvt_pk_bf16_f32 v28, v28, v29
	v_cvt_pk_bf16_f32 v29, v30, v31
	v_cvt_pk_bf16_f32 v30, v24, v25
	v_add_u32_e32 v24, 0xa0, v150
	global_store_dwordx4 v[148:149], v[110:113], off offset:256 nt
	v_cvt_pk_bf16_f32 v97, v92, v93
	v_mad_i64_i32 v[90:91], s[10:11], v90, s67, v[146:147]
	v_lshl_add_u64 v[110:111], v[106:107], 0, v[144:145]
	v_cvt_pk_bf16_f32 v78, v78, v79
	v_cvt_pk_bf16_f32 v79, v80, v81
	v_cvt_pk_bf16_f32 v80, v74, v75
	v_or_b32_e32 v74, 48, v150
	global_store_dwordx4 v[66:67], v[46:49], off offset:256 nt
	v_cvt_pk_bf16_f32 v31, v26, v27
	v_mad_i64_i32 v[24:25], s[10:11], v24, s67, v[146:147]
	v_lshl_add_u64 v[46:47], v[42:43], 0, v[144:145]
	v_cvt_pk_bf16_f32 v12, v12, v13
	v_cvt_pk_bf16_f32 v13, v14, v15
	v_cvt_pk_bf16_f32 v14, v8, v9
	v_add_u32_e32 v8, 0xb0, v150
	global_store_dwordx4 v[110:111], v[94:97], off offset:256 nt
	v_cvt_pk_bf16_f32 v81, v76, v77
	v_mad_i64_i32 v[74:75], s[10:11], v74, s67, v[146:147]
	v_lshl_add_u64 v[94:95], v[90:91], 0, v[144:145]
	global_store_dwordx4 v[46:47], v[28:31], off offset:256 nt
	v_cvt_pk_bf16_f32 v15, v10, v11
	v_mad_i64_i32 v[8:9], s[10:11], v8, s67, v[146:147]
	v_lshl_add_u64 v[28:29], v[24:25], 0, v[144:145]
	v_cvt_pk_bf16_f32 v126, v126, v127
	v_cvt_pk_bf16_f32 v127, v128, v129
	v_cvt_pk_bf16_f32 v128, v122, v123
	v_cvt_pk_bf16_f32 v129, v124, v125
	v_cvt_pk_bf16_f32 v106, v118, v119
	v_cvt_pk_bf16_f32 v107, v120, v121
	v_cvt_pk_bf16_f32 v108, v114, v115
	v_cvt_pk_bf16_f32 v109, v116, v117
	v_cvt_pk_bf16_f32 v90, v102, v103
	v_cvt_pk_bf16_f32 v91, v104, v105
	v_cvt_pk_bf16_f32 v92, v98, v99
	v_cvt_pk_bf16_f32 v93, v100, v101
	global_store_dwordx4 v[94:95], v[78:81], off offset:256 nt
	v_cvt_pk_bf16_f32 v76, v82, v83
	v_cvt_pk_bf16_f32 v77, v84, v85
	v_lshl_add_u64 v[78:79], v[74:75], 0, v[144:145]
	v_cvt_pk_bf16_f32 v74, v86, v87
	v_cvt_pk_bf16_f32 v75, v88, v89
	v_cvt_pk_bf16_f32 v73, v68, v69
	v_cvt_pk_bf16_f32 v62, v62, v63
	v_cvt_pk_bf16_f32 v63, v64, v65
	v_cvt_pk_bf16_f32 v64, v58, v59
	v_cvt_pk_bf16_f32 v65, v60, v61
	v_cvt_pk_bf16_f32 v42, v54, v55
	v_cvt_pk_bf16_f32 v43, v56, v57
	v_cvt_pk_bf16_f32 v44, v50, v51
	v_cvt_pk_bf16_f32 v45, v52, v53
	v_cvt_pk_bf16_f32 v24, v38, v39
	v_cvt_pk_bf16_f32 v25, v40, v41
	v_cvt_pk_bf16_f32 v26, v34, v35
	v_cvt_pk_bf16_f32 v27, v36, v37
	global_store_dwordx4 v[28:29], v[12:15], off offset:256 nt
	v_cvt_pk_bf16_f32 v10, v16, v17
	v_cvt_pk_bf16_f32 v11, v18, v19
	v_lshl_add_u64 v[12:13], v[8:9], 0, v[144:145]
	v_cvt_pk_bf16_f32 v8, v20, v21
	v_cvt_pk_bf16_f32 v9, v22, v23
	v_cvt_pk_bf16_f32 v4, v4, v5
	v_cvt_pk_bf16_f32 v5, v6, v7
	v_cvt_pk_bf16_f32 v6, v0, v1
	v_cvt_pk_bf16_f32 v7, v2, v3
	s_andn2_b64 vcc, exec, s[22:23]
	s_mov_b64 s[10:11], -1
	global_store_dwordx4 v[148:149], v[126:129], off nt
	global_store_dwordx4 v[110:111], v[106:109], off nt
	global_store_dwordx4 v[94:95], v[90:93], off nt
	global_store_dwordx4 v[78:79], v[74:77], off nt
	global_store_dwordx4 v[78:79], v[70:73], off offset:256 nt
	global_store_dwordx4 v[66:67], v[62:65], off nt
	global_store_dwordx4 v[46:47], v[42:45], off nt
	global_store_dwordx4 v[28:29], v[24:27], off nt
	global_store_dwordx4 v[12:13], v[8:11], off nt
	global_store_dwordx4 v[12:13], v[4:7], off offset:256 nt
	s_cbranch_vccnz .LBB0_258
	s_andn2_b64 vcc, exec, s[6:7]
	s_cbranch_vccnz .LBB0_257
	s_barrier
	s_branch .LBB0_257

; #define LAS __attribute__((address_space(3)))
; __device__ __forceinline__ unsigned pk2(float lo, float hi) { return pg8::cvt_pk_bf16(lo, hi); }
; __device__ __forceinline__ void item_store(const TItem& t, LAS float* scr, int lane) {
;     const int nblk = t.N / 64, kb = t.item / nblk, nb = t.item % nblk, k0 = 64 * kb, n0 = 64 * nb;
;     const int c = lane & 7, nn = lane >> 3;
; #pragma unroll
;     for (int j = 0; j < 8; ++j) { const int n = nn + 8 * j; const LAS float* s = scr + (8 * c) * 65 + n;
;         v4u o; o.x = pk2(s[0 * 65], s[1 * 65]); o.y = pk2(s[2 * 65], s[3 * 65]); o.z = pk2(s[4 * 65], s[5 * 65]); o.w = pk2(s[6 * 65], s[7 * 65]);
;         *(v4u*)(t.WT + (size_t)rowmap(t.mode, n0 + n) * t.K + k0 + 8 * c) = o; }
.LBB0_346:
	s_lshl_b32 s8, s16, 6
	s_waitcnt lgkmcnt(3)
	v_cvt_pk_bf16_f32 v4, v4, v5
	s_waitcnt lgkmcnt(2)
	v_cvt_pk_bf16_f32 v5, v6, v7
	s_waitcnt lgkmcnt(1)
	v_cvt_pk_bf16_f32 v6, v8, v9
	v_mad_u64_u32 v[8:9], s[16:17], v32, s37, 0
	s_waitcnt lgkmcnt(0)
	v_cvt_pk_bf16_f32 v7, v10, v11
	v_ashrrev_i32_e32 v11, 31, v32
	v_mov_b32_e32 v10, v9
	v_mad_u64_u32 v[10:11], s[16:17], v11, s37, v[10:11]
	v_mov_b32_e32 v9, v10
	s_ashr_i32 s9, s8, 31
	v_lshl_add_u64 v[8:9], v[8:9], 1, s[6:7]
	v_lshl_add_u64 v[8:9], s[8:9], 1, v[8:9]
	v_lshlrev_b32_e32 v32, 1, v2
	v_lshl_add_u64 v[8:9], v[8:9], 0, v[32:33]
	v_mov_b64_e32 v[102:103], v[8:9]
	global_store_dwordx4 v[8:9], v[4:7], off nt
	ds_read2_b32 v[4:5], v14 offset0:8 offset1:73
	ds_read2_b32 v[6:7], v14 offset0:138 offset1:203
	ds_read2_b32 v[8:9], v95 offset0:12 offset1:77
	ds_read2_b32 v[10:11], v95 offset0:142 offset1:207
	s_cmp_eq_u32 s38, 2
	s_cselect_b32 s8, 8, 16
	s_cselect_b32 s9, 40, 16
	s_mul_i32 s8, s8, s37
	s_mul_i32 s9, s9, s37
	s_mov_b32 s101, 0
	s_mov_b32 s100, s8
	ds_read2_b32 v[16:17], v14 offset0:16 offset1:81
	ds_read2_b32 v[18:19], v14 offset0:146 offset1:211
	ds_read2_b32 v[20:21], v95 offset0:20 offset1:85
	ds_read2_b32 v[22:23], v95 offset0:150 offset1:215
	ds_read2_b32 v[96:97], v14 offset0:24 offset1:89
	ds_read2_b32 v[98:99], v14 offset0:154 offset1:219
	ds_read2_b32 v[100:101], v95 offset0:28 offset1:93
	ds_read2_b32 v[24:25], v95 offset0:158 offset1:223
	s_waitcnt lgkmcnt(8)
	v_cvt_pk_bf16_f32 v4, v4, v5
	v_cvt_pk_bf16_f32 v5, v6, v7
	v_cvt_pk_bf16_f32 v6, v8, v9
	v_cvt_pk_bf16_f32 v7, v10, v11
	v_lshl_add_u64 v[102:103], v[102:103], 0, s[100:101]
	global_store_dwordx4 v[102:103], v[4:7], off nt
	ds_read2_b32 v[4:5], v14 offset0:32 offset1:97
	ds_read2_b32 v[6:7], v14 offset0:162 offset1:227
	ds_read2_b32 v[8:9], v95 offset0:36 offset1:101
	ds_read2_b32 v[10:11], v95 offset0:166 offset1:231
	s_waitcnt lgkmcnt(8)
	v_cvt_pk_bf16_f32 v16, v16, v17
	v_cvt_pk_bf16_f32 v17, v18, v19
	v_cvt_pk_bf16_f32 v18, v20, v21
	v_cvt_pk_bf16_f32 v19, v22, v23
	v_lshl_add_u64 v[102:103], v[102:103], 0, s[100:101]
	global_store_dwordx4 v[102:103], v[16:19], off nt
	ds_read2_b32 v[16:17], v14 offset0:40 offset1:105
	ds_read2_b32 v[18:19], v14 offset0:170 offset1:235
	ds_read2_b32 v[20:21], v95 offset0:44 offset1:109
	ds_read2_b32 v[22:23], v95 offset0:174 offset1:239
	s_waitcnt lgkmcnt(8)
	v_cvt_pk_bf16_f32 v96, v96, v97
	v_cvt_pk_bf16_f32 v97, v98, v99
	v_cvt_pk_bf16_f32 v98, v100, v101
	v_cvt_pk_bf16_f32 v99, v24, v25
	v_lshl_add_u64 v[102:103], v[102:103], 0, s[100:101]
	global_store_dwordx4 v[102:103], v[96:99], off nt
	ds_read2_b32 v[96:97], v14 offset0:48 offset1:113
	ds_read2_b32 v[98:99], v14 offset0:178 offset1:243
	ds_read2_b32 v[100:101], v95 offset0:52 offset1:117
	ds_read2_b32 v[24:25], v95 offset0:182 offset1:247
	s_mov_b32 s100, s9
	s_waitcnt lgkmcnt(8)
	v_cvt_pk_bf16_f32 v4, v4, v5
	v_cvt_pk_bf16_f32 v5, v6, v7
	v_cvt_pk_bf16_f32 v6, v8, v9
	v_cvt_pk_bf16_f32 v7, v10, v11
	v_lshl_add_u64 v[102:103], v[102:103], 0, s[100:101]
	global_store_dwordx4 v[102:103], v[4:7], off nt
	s_mov_b32 s100, s8
	ds_read2_b32 v[4:5], v14 offset0:56 offset1:121
	ds_read2_b32 v[6:7], v14 offset0:186 offset1:251
	ds_read2_b32 v[8:9], v95 offset0:60 offset1:125
	ds_read2_b32 v[10:11], v95 offset0:190 offset1:255
	s_waitcnt lgkmcnt(8)
	v_cvt_pk_bf16_f32 v16, v16, v17
	v_cvt_pk_bf16_f32 v17, v18, v19
	v_cvt_pk_bf16_f32 v18, v20, v21
	v_cvt_pk_bf16_f32 v19, v22, v23
	v_lshl_add_u64 v[102:103], v[102:103], 0, s[100:101]
	global_store_dwordx4 v[102:103], v[16:19], off nt
	s_waitcnt lgkmcnt(4)
	v_cvt_pk_bf16_f32 v96, v96, v97
	v_cvt_pk_bf16_f32 v97, v98, v99
	v_cvt_pk_bf16_f32 v98, v100, v101
	v_cvt_pk_bf16_f32 v99, v24, v25
	v_lshl_add_u64 v[102:103], v[102:103], 0, s[100:101]
	global_store_dwordx4 v[102:103], v[96:99], off nt
	s_waitcnt lgkmcnt(0)
	v_cvt_pk_bf16_f32 v4, v4, v5
	v_cvt_pk_bf16_f32 v5, v6, v7
	v_cvt_pk_bf16_f32 v6, v8, v9
	v_cvt_pk_bf16_f32 v7, v10, v11
	v_lshl_add_u64 v[102:103], v[102:103], 0, s[100:101]
	global_store_dwordx4 v[102:103], v[4:7], off nt
	s_branch .Lconv_tail_g1
